# UP (SwiGLU) epilogue re-emitted by hand on top of the packed RES sum-of-squares: the four 1+e adds of a quad as two v_pk_add_f32, exp/add/rcp in place in the gate registers, rstd pairs read up front,
# speedup vs baseline: 1.0206x; 1.0114x over previous
.LBB0_286:
	v_lshl_add_u32 v178, s25, 10, v153
	ds_read2_b32 v[180:181], v178 offset1:16
	ds_read2_b32 v[182:183], v178 offset0:32 offset1:48
	ds_read2_b32 v[184:185], v178 offset0:128 offset1:144
	ds_read2_b32 v[186:187], v178 offset0:160 offset1:176
	v_mov_b32_e32 v188, 1.0
	v_lshl_or_b32 v194, s21, 7, v154
	v_lshl_add_u32 v196, s24, 8, v131
	v_ashrrev_i32_e32 v195, 31, v194
	v_mov_b64_e32 v[198:199], s[80:81]
	v_lshlrev_b64 v[194:195], 1, v[194:195]
	s_waitcnt lgkmcnt(3)
	v_mul_f32_e32 v190, 0xbfb8aa3b, v180
	v_mul_f32_e32 v192, v180, v180
	v_pk_mul_f32 v[122:123], v[126:127], v[122:123]
	v_pk_mul_f32 v[124:125], v[128:129], v[124:125]
	v_pk_mul_f32 v[114:115], v[118:119], v[114:115]
	v_pk_mul_f32 v[116:117], v[120:121], v[116:117]
	v_pk_mul_f32 v[126:127], v[126:127], v[190:191] op_sel_hi:[1,0]
	v_pk_mul_f32 v[128:129], v[128:129], v[190:191] op_sel_hi:[1,0]
	v_pk_mul_f32 v[118:119], v[118:119], v[190:191] op_sel_hi:[1,0]
	v_pk_mul_f32 v[120:121], v[120:121], v[190:191] op_sel_hi:[1,0]
	v_exp_f32_e32 v126, v126
	v_exp_f32_e32 v127, v127
	v_exp_f32_e32 v128, v128
	v_exp_f32_e32 v129, v129
	v_exp_f32_e32 v118, v118
	v_exp_f32_e32 v119, v119
	v_exp_f32_e32 v120, v120
	v_exp_f32_e32 v121, v121
	v_pk_add_f32 v[126:127], v[126:127], v[188:189] op_sel_hi:[1,0]
	v_pk_add_f32 v[128:129], v[128:129], v[188:189] op_sel_hi:[1,0]
	v_pk_add_f32 v[118:119], v[118:119], v[188:189] op_sel_hi:[1,0]
	v_pk_add_f32 v[120:121], v[120:121], v[188:189] op_sel_hi:[1,0]
	v_rcp_f32_e32 v126, v126
	v_rcp_f32_e32 v127, v127
	v_rcp_f32_e32 v128, v128
	v_rcp_f32_e32 v129, v129
	v_rcp_f32_e32 v118, v118
	v_rcp_f32_e32 v119, v119
	v_rcp_f32_e32 v120, v120
	v_rcp_f32_e32 v121, v121
	v_pk_mul_f32 v[122:123], v[122:123], v[192:193] op_sel_hi:[1,0]
	v_pk_mul_f32 v[124:125], v[124:125], v[192:193] op_sel_hi:[1,0]
	v_pk_mul_f32 v[114:115], v[114:115], v[192:193] op_sel_hi:[1,0]
	v_pk_mul_f32 v[116:117], v[116:117], v[192:193] op_sel_hi:[1,0]
	v_add_u32_e32 v197, 0x0, v196
	v_mad_i64_i32 v[200:201], s[22:23], v197, s34, v[198:199]
	v_pk_mul_f32 v[122:123], v[122:123], v[126:127]
	v_pk_mul_f32 v[124:125], v[124:125], v[128:129]
	v_pk_mul_f32 v[114:115], v[114:115], v[118:119]
	v_pk_mul_f32 v[116:117], v[116:117], v[120:121]
	v_lshl_add_u64 v[200:201], v[200:201], 0, v[194:195]
	v_cvt_pk_bf16_f32 v118, v122, v123
	v_cvt_pk_bf16_f32 v119, v124, v125
	v_cvt_pk_bf16_f32 v120, v114, v115
	v_cvt_pk_bf16_f32 v121, v116, v117
	global_store_dwordx4 v[200:201], v[118:121], off nt
	v_mul_f32_e32 v190, 0xbfb8aa3b, v181
	v_mul_f32_e32 v192, v181, v181
	v_pk_mul_f32 v[106:107], v[110:111], v[106:107]
	v_pk_mul_f32 v[108:109], v[112:113], v[108:109]
	v_pk_mul_f32 v[98:99], v[102:103], v[98:99]
	v_pk_mul_f32 v[100:101], v[104:105], v[100:101]
	v_pk_mul_f32 v[110:111], v[110:111], v[190:191] op_sel_hi:[1,0]
	v_pk_mul_f32 v[112:113], v[112:113], v[190:191] op_sel_hi:[1,0]
	v_pk_mul_f32 v[102:103], v[102:103], v[190:191] op_sel_hi:[1,0]
	v_pk_mul_f32 v[104:105], v[104:105], v[190:191] op_sel_hi:[1,0]
	v_exp_f32_e32 v110, v110
	v_exp_f32_e32 v111, v111
	v_exp_f32_e32 v112, v112
	v_exp_f32_e32 v113, v113
	v_exp_f32_e32 v102, v102
	v_exp_f32_e32 v103, v103
	v_exp_f32_e32 v104, v104
	v_exp_f32_e32 v105, v105
	v_pk_add_f32 v[110:111], v[110:111], v[188:189] op_sel_hi:[1,0]
	v_pk_add_f32 v[112:113], v[112:113], v[188:189] op_sel_hi:[1,0]
	v_pk_add_f32 v[102:103], v[102:103], v[188:189] op_sel_hi:[1,0]
	v_pk_add_f32 v[104:105], v[104:105], v[188:189] op_sel_hi:[1,0]
	v_rcp_f32_e32 v110, v110
	v_rcp_f32_e32 v111, v111
	v_rcp_f32_e32 v112, v112
	v_rcp_f32_e32 v113, v113
	v_rcp_f32_e32 v102, v102
	v_rcp_f32_e32 v103, v103
	v_rcp_f32_e32 v104, v104
	v_rcp_f32_e32 v105, v105
	v_pk_mul_f32 v[106:107], v[106:107], v[192:193] op_sel_hi:[1,0]
	v_pk_mul_f32 v[108:109], v[108:109], v[192:193] op_sel_hi:[1,0]
	v_pk_mul_f32 v[98:99], v[98:99], v[192:193] op_sel_hi:[1,0]
	v_pk_mul_f32 v[100:101], v[100:101], v[192:193] op_sel_hi:[1,0]
	v_add_u32_e32 v197, 0x10, v196
	v_mad_i64_i32 v[200:201], s[22:23], v197, s34, v[198:199]
	v_pk_mul_f32 v[106:107], v[106:107], v[110:111]
	v_pk_mul_f32 v[108:109], v[108:109], v[112:113]
	v_pk_mul_f32 v[98:99], v[98:99], v[102:103]
	v_pk_mul_f32 v[100:101], v[100:101], v[104:105]
	v_lshl_add_u64 v[200:201], v[200:201], 0, v[194:195]
	v_cvt_pk_bf16_f32 v102, v106, v107
	v_cvt_pk_bf16_f32 v103, v108, v109
	v_cvt_pk_bf16_f32 v104, v98, v99
	v_cvt_pk_bf16_f32 v105, v100, v101
	global_store_dwordx4 v[200:201], v[102:105], off nt
	s_waitcnt lgkmcnt(2)
	v_mul_f32_e32 v190, 0xbfb8aa3b, v182
	v_mul_f32_e32 v192, v182, v182
	v_pk_mul_f32 v[90:91], v[94:95], v[90:91]
	v_pk_mul_f32 v[92:93], v[96:97], v[92:93]
	v_pk_mul_f32 v[82:83], v[86:87], v[82:83]
	v_pk_mul_f32 v[84:85], v[88:89], v[84:85]
	v_pk_mul_f32 v[94:95], v[94:95], v[190:191] op_sel_hi:[1,0]
	v_pk_mul_f32 v[96:97], v[96:97], v[190:191] op_sel_hi:[1,0]
	v_pk_mul_f32 v[86:87], v[86:87], v[190:191] op_sel_hi:[1,0]
	v_pk_mul_f32 v[88:89], v[88:89], v[190:191] op_sel_hi:[1,0]
	v_exp_f32_e32 v94, v94
	v_exp_f32_e32 v95, v95
	v_exp_f32_e32 v96, v96
	v_exp_f32_e32 v97, v97
	v_exp_f32_e32 v86, v86
	v_exp_f32_e32 v87, v87
	v_exp_f32_e32 v88, v88
	v_exp_f32_e32 v89, v89
	v_pk_add_f32 v[94:95], v[94:95], v[188:189] op_sel_hi:[1,0]
	v_pk_add_f32 v[96:97], v[96:97], v[188:189] op_sel_hi:[1,0]
	v_pk_add_f32 v[86:87], v[86:87], v[188:189] op_sel_hi:[1,0]
	v_pk_add_f32 v[88:89], v[88:89], v[188:189] op_sel_hi:[1,0]
	v_rcp_f32_e32 v94, v94
	v_rcp_f32_e32 v95, v95
	v_rcp_f32_e32 v96, v96
	v_rcp_f32_e32 v97, v97
	v_rcp_f32_e32 v86, v86
	v_rcp_f32_e32 v87, v87
	v_rcp_f32_e32 v88, v88
	v_rcp_f32_e32 v89, v89
	v_pk_mul_f32 v[90:91], v[90:91], v[192:193] op_sel_hi:[1,0]
	v_pk_mul_f32 v[92:93], v[92:93], v[192:193] op_sel_hi:[1,0]
	v_pk_mul_f32 v[82:83], v[82:83], v[192:193] op_sel_hi:[1,0]
	v_pk_mul_f32 v[84:85], v[84:85], v[192:193] op_sel_hi:[1,0]
	v_add_u32_e32 v197, 0x20, v196
	v_mad_i64_i32 v[200:201], s[22:23], v197, s34, v[198:199]
	v_pk_mul_f32 v[90:91], v[90:91], v[94:95]
	v_pk_mul_f32 v[92:93], v[92:93], v[96:97]
	v_pk_mul_f32 v[82:83], v[82:83], v[86:87]
	v_pk_mul_f32 v[84:85], v[84:85], v[88:89]
	v_lshl_add_u64 v[200:201], v[200:201], 0, v[194:195]
	v_cvt_pk_bf16_f32 v86, v90, v91
	v_cvt_pk_bf16_f32 v87, v92, v93
	v_cvt_pk_bf16_f32 v88, v82, v83
	v_cvt_pk_bf16_f32 v89, v84, v85
	global_store_dwordx4 v[200:201], v[86:89], off nt
	v_mul_f32_e32 v190, 0xbfb8aa3b, v183
	v_mul_f32_e32 v192, v183, v183
	v_pk_mul_f32 v[74:75], v[78:79], v[74:75]
	v_pk_mul_f32 v[76:77], v[80:81], v[76:77]
	v_pk_mul_f32 v[66:67], v[70:71], v[66:67]
	v_pk_mul_f32 v[68:69], v[72:73], v[68:69]
	v_pk_mul_f32 v[78:79], v[78:79], v[190:191] op_sel_hi:[1,0]
	v_pk_mul_f32 v[80:81], v[80:81], v[190:191] op_sel_hi:[1,0]
	v_pk_mul_f32 v[70:71], v[70:71], v[190:191] op_sel_hi:[1,0]
	v_pk_mul_f32 v[72:73], v[72:73], v[190:191] op_sel_hi:[1,0]
	v_exp_f32_e32 v78, v78
	v_exp_f32_e32 v79, v79
	v_exp_f32_e32 v80, v80
	v_exp_f32_e32 v81, v81
	v_exp_f32_e32 v70, v70
	v_exp_f32_e32 v71, v71
	v_exp_f32_e32 v72, v72
	v_exp_f32_e32 v73, v73
	v_pk_add_f32 v[78:79], v[78:79], v[188:189] op_sel_hi:[1,0]
	v_pk_add_f32 v[80:81], v[80:81], v[188:189] op_sel_hi:[1,0]
	v_pk_add_f32 v[70:71], v[70:71], v[188:189] op_sel_hi:[1,0]
	v_pk_add_f32 v[72:73], v[72:73], v[188:189] op_sel_hi:[1,0]
	v_rcp_f32_e32 v78, v78
	v_rcp_f32_e32 v79, v79
	v_rcp_f32_e32 v80, v80
	v_rcp_f32_e32 v81, v81
	v_rcp_f32_e32 v70, v70
	v_rcp_f32_e32 v71, v71
	v_rcp_f32_e32 v72, v72
	v_rcp_f32_e32 v73, v73
	v_pk_mul_f32 v[74:75], v[74:75], v[192:193] op_sel_hi:[1,0]
	v_pk_mul_f32 v[76:77], v[76:77], v[192:193] op_sel_hi:[1,0]
	v_pk_mul_f32 v[66:67], v[66:67], v[192:193] op_sel_hi:[1,0]
	v_pk_mul_f32 v[68:69], v[68:69], v[192:193] op_sel_hi:[1,0]
	v_add_u32_e32 v197, 0x30, v196
	v_mad_i64_i32 v[200:201], s[22:23], v197, s34, v[198:199]
	v_pk_mul_f32 v[74:75], v[74:75], v[78:79]
	v_pk_mul_f32 v[76:77], v[76:77], v[80:81]
	v_pk_mul_f32 v[66:67], v[66:67], v[70:71]
	v_pk_mul_f32 v[68:69], v[68:69], v[72:73]
	v_lshl_add_u64 v[200:201], v[200:201], 0, v[194:195]
	v_cvt_pk_bf16_f32 v70, v74, v75
	v_cvt_pk_bf16_f32 v71, v76, v77
	v_cvt_pk_bf16_f32 v72, v66, v67
	v_cvt_pk_bf16_f32 v73, v68, v69
	global_store_dwordx4 v[200:201], v[70:73], off nt
	s_waitcnt lgkmcnt(1)
	v_mul_f32_e32 v190, 0xbfb8aa3b, v184
	v_mul_f32_e32 v192, v184, v184
	v_pk_mul_f32 v[58:59], v[62:63], v[58:59]
	v_pk_mul_f32 v[60:61], v[64:65], v[60:61]
	v_pk_mul_f32 v[50:51], v[54:55], v[50:51]
	v_pk_mul_f32 v[52:53], v[56:57], v[52:53]
	v_pk_mul_f32 v[62:63], v[62:63], v[190:191] op_sel_hi:[1,0]
	v_pk_mul_f32 v[64:65], v[64:65], v[190:191] op_sel_hi:[1,0]
	v_pk_mul_f32 v[54:55], v[54:55], v[190:191] op_sel_hi:[1,0]
	v_pk_mul_f32 v[56:57], v[56:57], v[190:191] op_sel_hi:[1,0]
	v_exp_f32_e32 v62, v62
	v_exp_f32_e32 v63, v63
	v_exp_f32_e32 v64, v64
	v_exp_f32_e32 v65, v65
	v_exp_f32_e32 v54, v54
	v_exp_f32_e32 v55, v55
	v_exp_f32_e32 v56, v56
	v_exp_f32_e32 v57, v57
	v_pk_add_f32 v[62:63], v[62:63], v[188:189] op_sel_hi:[1,0]
	v_pk_add_f32 v[64:65], v[64:65], v[188:189] op_sel_hi:[1,0]
	v_pk_add_f32 v[54:55], v[54:55], v[188:189] op_sel_hi:[1,0]
	v_pk_add_f32 v[56:57], v[56:57], v[188:189] op_sel_hi:[1,0]
	v_rcp_f32_e32 v62, v62
	v_rcp_f32_e32 v63, v63
	v_rcp_f32_e32 v64, v64
	v_rcp_f32_e32 v65, v65
	v_rcp_f32_e32 v54, v54
	v_rcp_f32_e32 v55, v55
	v_rcp_f32_e32 v56, v56
	v_rcp_f32_e32 v57, v57
	v_pk_mul_f32 v[58:59], v[58:59], v[192:193] op_sel_hi:[1,0]
	v_pk_mul_f32 v[60:61], v[60:61], v[192:193] op_sel_hi:[1,0]
	v_pk_mul_f32 v[50:51], v[50:51], v[192:193] op_sel_hi:[1,0]
	v_pk_mul_f32 v[52:53], v[52:53], v[192:193] op_sel_hi:[1,0]
	v_add_u32_e32 v197, 0x80, v196
	v_mad_i64_i32 v[200:201], s[22:23], v197, s34, v[198:199]
	v_pk_mul_f32 v[58:59], v[58:59], v[62:63]
	v_pk_mul_f32 v[60:61], v[60:61], v[64:65]
	v_pk_mul_f32 v[50:51], v[50:51], v[54:55]
	v_pk_mul_f32 v[52:53], v[52:53], v[56:57]
	v_lshl_add_u64 v[200:201], v[200:201], 0, v[194:195]
	v_cvt_pk_bf16_f32 v54, v58, v59
	v_cvt_pk_bf16_f32 v55, v60, v61
	v_cvt_pk_bf16_f32 v56, v50, v51
	v_cvt_pk_bf16_f32 v57, v52, v53
	global_store_dwordx4 v[200:201], v[54:57], off nt
	v_mul_f32_e32 v190, 0xbfb8aa3b, v185
	v_mul_f32_e32 v192, v185, v185
	v_pk_mul_f32 v[42:43], v[46:47], v[42:43]
	v_pk_mul_f32 v[44:45], v[48:49], v[44:45]
	v_pk_mul_f32 v[34:35], v[38:39], v[34:35]
	v_pk_mul_f32 v[36:37], v[40:41], v[36:37]
	v_pk_mul_f32 v[46:47], v[46:47], v[190:191] op_sel_hi:[1,0]
	v_pk_mul_f32 v[48:49], v[48:49], v[190:191] op_sel_hi:[1,0]
	v_pk_mul_f32 v[38:39], v[38:39], v[190:191] op_sel_hi:[1,0]
	v_pk_mul_f32 v[40:41], v[40:41], v[190:191] op_sel_hi:[1,0]
	v_exp_f32_e32 v46, v46
	v_exp_f32_e32 v47, v47
	v_exp_f32_e32 v48, v48
	v_exp_f32_e32 v49, v49
	v_exp_f32_e32 v38, v38
	v_exp_f32_e32 v39, v39
	v_exp_f32_e32 v40, v40
	v_exp_f32_e32 v41, v41
	v_pk_add_f32 v[46:47], v[46:47], v[188:189] op_sel_hi:[1,0]
	v_pk_add_f32 v[48:49], v[48:49], v[188:189] op_sel_hi:[1,0]
	v_pk_add_f32 v[38:39], v[38:39], v[188:189] op_sel_hi:[1,0]
	v_pk_add_f32 v[40:41], v[40:41], v[188:189] op_sel_hi:[1,0]
	v_rcp_f32_e32 v46, v46
	v_rcp_f32_e32 v47, v47
	v_rcp_f32_e32 v48, v48
	v_rcp_f32_e32 v49, v49
	v_rcp_f32_e32 v38, v38
	v_rcp_f32_e32 v39, v39
	v_rcp_f32_e32 v40, v40
	v_rcp_f32_e32 v41, v41
	v_pk_mul_f32 v[42:43], v[42:43], v[192:193] op_sel_hi:[1,0]
	v_pk_mul_f32 v[44:45], v[44:45], v[192:193] op_sel_hi:[1,0]
	v_pk_mul_f32 v[34:35], v[34:35], v[192:193] op_sel_hi:[1,0]
	v_pk_mul_f32 v[36:37], v[36:37], v[192:193] op_sel_hi:[1,0]
	v_add_u32_e32 v197, 0x90, v196
	v_mad_i64_i32 v[200:201], s[22:23], v197, s34, v[198:199]
	v_pk_mul_f32 v[42:43], v[42:43], v[46:47]
	v_pk_mul_f32 v[44:45], v[44:45], v[48:49]
	v_pk_mul_f32 v[34:35], v[34:35], v[38:39]
	v_pk_mul_f32 v[36:37], v[36:37], v[40:41]
	v_lshl_add_u64 v[200:201], v[200:201], 0, v[194:195]
	v_cvt_pk_bf16_f32 v38, v42, v43
	v_cvt_pk_bf16_f32 v39, v44, v45
	v_cvt_pk_bf16_f32 v40, v34, v35
	v_cvt_pk_bf16_f32 v41, v36, v37
	global_store_dwordx4 v[200:201], v[38:41], off nt
	s_waitcnt lgkmcnt(0)
	v_mul_f32_e32 v190, 0xbfb8aa3b, v186
	v_mul_f32_e32 v192, v186, v186
	v_pk_mul_f32 v[26:27], v[30:31], v[26:27]
	v_pk_mul_f32 v[28:29], v[32:33], v[28:29]
	v_pk_mul_f32 v[18:19], v[22:23], v[18:19]
	v_pk_mul_f32 v[20:21], v[24:25], v[20:21]
	v_pk_mul_f32 v[30:31], v[30:31], v[190:191] op_sel_hi:[1,0]
	v_pk_mul_f32 v[32:33], v[32:33], v[190:191] op_sel_hi:[1,0]
	v_pk_mul_f32 v[22:23], v[22:23], v[190:191] op_sel_hi:[1,0]
	v_pk_mul_f32 v[24:25], v[24:25], v[190:191] op_sel_hi:[1,0]
	v_exp_f32_e32 v30, v30
	v_exp_f32_e32 v31, v31
	v_exp_f32_e32 v32, v32
	v_exp_f32_e32 v33, v33
	v_exp_f32_e32 v22, v22
	v_exp_f32_e32 v23, v23
	v_exp_f32_e32 v24, v24
	v_exp_f32_e32 v25, v25
	v_pk_add_f32 v[30:31], v[30:31], v[188:189] op_sel_hi:[1,0]
	v_pk_add_f32 v[32:33], v[32:33], v[188:189] op_sel_hi:[1,0]
	v_pk_add_f32 v[22:23], v[22:23], v[188:189] op_sel_hi:[1,0]
	v_pk_add_f32 v[24:25], v[24:25], v[188:189] op_sel_hi:[1,0]
	v_rcp_f32_e32 v30, v30
	v_rcp_f32_e32 v31, v31
	v_rcp_f32_e32 v32, v32
	v_rcp_f32_e32 v33, v33
	v_rcp_f32_e32 v22, v22
	v_rcp_f32_e32 v23, v23
	v_rcp_f32_e32 v24, v24
	v_rcp_f32_e32 v25, v25
	v_pk_mul_f32 v[26:27], v[26:27], v[192:193] op_sel_hi:[1,0]
	v_pk_mul_f32 v[28:29], v[28:29], v[192:193] op_sel_hi:[1,0]
	v_pk_mul_f32 v[18:19], v[18:19], v[192:193] op_sel_hi:[1,0]
	v_pk_mul_f32 v[20:21], v[20:21], v[192:193] op_sel_hi:[1,0]
	v_add_u32_e32 v197, 0xa0, v196
	v_mad_i64_i32 v[200:201], s[22:23], v197, s34, v[198:199]
	v_pk_mul_f32 v[26:27], v[26:27], v[30:31]
	v_pk_mul_f32 v[28:29], v[28:29], v[32:33]
	v_pk_mul_f32 v[18:19], v[18:19], v[22:23]
	v_pk_mul_f32 v[20:21], v[20:21], v[24:25]
	v_lshl_add_u64 v[200:201], v[200:201], 0, v[194:195]
	v_cvt_pk_bf16_f32 v22, v26, v27
	v_cvt_pk_bf16_f32 v23, v28, v29
	v_cvt_pk_bf16_f32 v24, v18, v19
	v_cvt_pk_bf16_f32 v25, v20, v21
	global_store_dwordx4 v[200:201], v[22:25], off nt
	v_mul_f32_e32 v190, 0xbfb8aa3b, v187
	v_mul_f32_e32 v192, v187, v187
	v_pk_mul_f32 v[10:11], v[14:15], v[10:11]
	v_pk_mul_f32 v[12:13], v[16:17], v[12:13]
	v_pk_mul_f32 v[2:3], v[6:7], v[2:3]
	v_pk_mul_f32 v[4:5], v[8:9], v[4:5]
	v_pk_mul_f32 v[14:15], v[14:15], v[190:191] op_sel_hi:[1,0]
	v_pk_mul_f32 v[16:17], v[16:17], v[190:191] op_sel_hi:[1,0]
	v_pk_mul_f32 v[6:7], v[6:7], v[190:191] op_sel_hi:[1,0]
	v_pk_mul_f32 v[8:9], v[8:9], v[190:191] op_sel_hi:[1,0]
	v_exp_f32_e32 v14, v14
	v_exp_f32_e32 v15, v15
	v_exp_f32_e32 v16, v16
	v_exp_f32_e32 v17, v17
	v_exp_f32_e32 v6, v6
	v_exp_f32_e32 v7, v7
	v_exp_f32_e32 v8, v8
	v_exp_f32_e32 v9, v9
	v_pk_add_f32 v[14:15], v[14:15], v[188:189] op_sel_hi:[1,0]
	v_pk_add_f32 v[16:17], v[16:17], v[188:189] op_sel_hi:[1,0]
	v_pk_add_f32 v[6:7], v[6:7], v[188:189] op_sel_hi:[1,0]
	v_pk_add_f32 v[8:9], v[8:9], v[188:189] op_sel_hi:[1,0]
	v_rcp_f32_e32 v14, v14
	v_rcp_f32_e32 v15, v15
	v_rcp_f32_e32 v16, v16
	v_rcp_f32_e32 v17, v17
	v_rcp_f32_e32 v6, v6
	v_rcp_f32_e32 v7, v7
	v_rcp_f32_e32 v8, v8
	v_rcp_f32_e32 v9, v9
	v_pk_mul_f32 v[10:11], v[10:11], v[192:193] op_sel_hi:[1,0]
	v_pk_mul_f32 v[12:13], v[12:13], v[192:193] op_sel_hi:[1,0]
	v_pk_mul_f32 v[2:3], v[2:3], v[192:193] op_sel_hi:[1,0]
	v_pk_mul_f32 v[4:5], v[4:5], v[192:193] op_sel_hi:[1,0]
	v_add_u32_e32 v197, 0xb0, v196
	v_mad_i64_i32 v[200:201], s[22:23], v197, s34, v[198:199]
	v_pk_mul_f32 v[10:11], v[10:11], v[14:15]
	v_pk_mul_f32 v[12:13], v[12:13], v[16:17]
	v_pk_mul_f32 v[2:3], v[2:3], v[6:7]
	v_pk_mul_f32 v[4:5], v[4:5], v[8:9]
	v_lshl_add_u64 v[200:201], v[200:201], 0, v[194:195]
	v_cvt_pk_bf16_f32 v6, v10, v11
	v_cvt_pk_bf16_f32 v7, v12, v13
	v_cvt_pk_bf16_f32 v8, v2, v3
	v_cvt_pk_bf16_f32 v9, v4, v5
	s_andn2_b64 vcc, exec, s[6:7]
	s_mov_b64 s[6:7], -1
	global_store_dwordx4 v[200:201], v[6:9], off nt
	s_cbranch_vccnz .LBB0_279
	s_andn2_b64 vcc, exec, s[8:9]
	s_cbranch_vccnz .LBB0_278
	s_barrier
	s_branch .LBB0_278
